# GU: per-phase LDS tables of K=-log2e*rstd and C=1/rstd^2 built with the rstd table; tile epilogue reads them instead of recomputing 2 mul + 1 rcp per site
# speedup vs baseline: 1.0023x; 1.0023x over previous
.LBB0_780:
	s_waitcnt vmcnt(0)
	v_mov_b32_e32 v0, v156
	s_cmp_gt_i32 s4, -1
	s_cselect_b64 s[8:9], -1, 0
	v_cmp_gt_i32_e32 vcc, s55, v0
	s_and_b64 s[18:19], s[8:9], vcc
	s_and_saveexec_b64 s[8:9], s[18:19]
	s_cbranch_execz .LBB0_782
	v_lshl_add_u32 v2, s4, 8, v0
	v_ashrrev_i32_e32 v3, 31, v2
	v_lshlrev_b64 v[2:3], 6, v[2:3]
	v_lshl_add_u64 v[14:15], s[94:95], 0, v[2:3]
	global_load_dwordx4 v[2:5], v[14:15], off
	global_load_dwordx4 v[6:9], v[14:15], off offset:16
	global_load_dwordx4 v[10:13], v[14:15], off offset:32
	s_nop 0
	global_load_dwordx4 v[14:17], v[14:15], off offset:48
	v_lshl_add_u32 v0, v0, 2, 0
	v_add_u32_e32 v0, 0x20000, v0
	s_waitcnt vmcnt(0)
	v_mov_b32_e32 v18, v3
	v_mov_b32_e32 v19, v4
	v_mov_b32_e32 v3, v5
	v_mov_b32_e32 v4, v7
	v_mov_b32_e32 v5, v8
	v_mov_b32_e32 v7, v9
	v_pk_add_f32 v[2:3], v[18:19], v[2:3]
	v_pk_add_f32 v[4:5], v[4:5], v[6:7]
	v_pk_add_f32 v[2:3], v[2:3], v[2:3] op_sel:[0,1] op_sel_hi:[1,0]
	v_pk_add_f32 v[4:5], v[4:5], v[4:5] op_sel:[0,1] op_sel_hi:[1,0]
	v_add_f32_e32 v8, v10, v11
	v_add_f32_e32 v10, v12, v13
	v_mov_b32_e32 v9, v16
	v_mov_b32_e32 v11, v17
	v_mov_b32_e32 v3, v14
	v_mov_b32_e32 v5, v15
	v_pk_add_f32 v[6:7], v[8:9], v[10:11]
	v_pk_add_f32 v[2:3], v[2:3], v[4:5]
	s_nop 0
	v_pk_add_f32 v[2:3], v[2:3], v[6:7]
	s_waitcnt lgkmcnt(0)
	v_add_f32_e32 v1, v2, v3
	v_fmamk_f32 v1, v1, 0x3a800000, v193
	v_mul_f32_e32 v2, 0x4b800000, v1
	v_cmp_gt_f32_e32 vcc, s40, v1
	s_nop 1
	v_cndmask_b32_e32 v1, v1, v2, vcc
	v_rsq_f32_e32 v1, v1
	s_nop 0
	v_mul_f32_e32 v2, 0x45800000, v1
	v_cndmask_b32_e32 v1, v1, v2, vcc
	ds_write_b32 v0, v1
	v_mul_f32_e32 v2, 0xbfb8aa3b, v1
	v_mul_f32_e32 v3, v1, v1
	v_rcp_f32_e32 v3, v3
	ds_write_b32 v0, v2 offset:1024
	s_nop 0
	ds_write_b32 v0, v3 offset:2048

.LBB0_788:
	s_waitcnt lgkmcnt(0)
	v_mul_f32_e32 v8, v8, v12
	v_mul_f32_e32 v9, v9, v13
	v_mul_f32_e32 v10, v10, v14
	v_mul_f32_e32 v11, v11, v15
	v_mul_f32_e32 v0, v0, v4
	v_mul_f32_e32 v1, v1, v5
	v_mul_f32_e32 v2, v2, v6
	v_mul_f32_e32 v3, v3, v7
	v_mul_f32_e32 v12, v221, v12
	v_mul_f32_e32 v13, v221, v13
	v_mul_f32_e32 v14, v221, v14
	v_mul_f32_e32 v15, v221, v15
	v_mul_f32_e32 v4, v221, v4
	v_mul_f32_e32 v5, v221, v5
	v_mul_f32_e32 v6, v221, v6
	v_mul_f32_e32 v7, v221, v7
	v_exp_f32_e32 v12, v12
	v_exp_f32_e32 v13, v13
	v_exp_f32_e32 v14, v14
	v_exp_f32_e32 v15, v15
	v_exp_f32_e32 v4, v4
	v_exp_f32_e32 v5, v5
	v_exp_f32_e32 v6, v6
	v_exp_f32_e32 v7, v7
	v_fma_f32 v12, v12, v237, v237
	v_fma_f32 v13, v13, v237, v237
	v_fma_f32 v14, v14, v237, v237
	v_fma_f32 v15, v15, v237, v237
	v_fma_f32 v4, v4, v237, v237
	v_fma_f32 v5, v5, v237, v237
	v_fma_f32 v6, v6, v237, v237
	v_fma_f32 v7, v7, v237, v237
	v_rcp_f32_e32 v12, v12
	v_rcp_f32_e32 v13, v13
	v_rcp_f32_e32 v14, v14
	v_rcp_f32_e32 v15, v15
	v_rcp_f32_e32 v4, v4
	v_rcp_f32_e32 v5, v5
	v_rcp_f32_e32 v6, v6
	v_rcp_f32_e32 v7, v7
	v_mul_f32_e32 v8, v8, v12
	v_mul_f32_e32 v9, v9, v13
	v_mul_f32_e32 v10, v10, v14
	v_mul_f32_e32 v11, v11, v15
	v_mul_f32_e32 v0, v0, v4
	v_mul_f32_e32 v1, v1, v5
	v_mul_f32_e32 v2, v2, v6
	v_mul_f32_e32 v3, v3, v7
	v_cvt_pk_bf16_f32 v12, v8, v9
	v_cvt_pk_bf16_f32 v13, v10, v11
	v_cvt_pk_bf16_f32 v14, v0, v1
	v_cvt_pk_bf16_f32 v15, v2, v3
	s_and_b64 vcc, exec, s[6:7]
	s_mov_b32 s8, s18
	s_mov_b32 s28, s20
	s_mov_b64 s[62:63], s[24:25]
	s_mov_b64 s[58:59], s[22:23]
	s_mov_b32 s1, 0xf2000
	buffer_store_dwordx4 v[12:15], v222, s[36:39], s1 offen sc1
	s_cbranch_vccnz .LBB0_825

.Lzp_exit3:
	s_lshl_b32 s19, s28, 8
	v_add_u32_e32 v138, s19, v141
	ds_read_b32 v140, v143 offset:1024
	ds_read_b32 v230, v143 offset:2048
	ds_read_b32 v215, v143 offset:1088
	ds_read_b32 v231, v143 offset:2112
	ds_read_b32 v216, v143 offset:1152
	ds_read_b32 v232, v143 offset:2176
	ds_read_b32 v217, v143 offset:1216
	ds_read_b32 v233, v143 offset:2240
	ds_read_b32 v218, v143 offset:1536
	ds_read_b32 v234, v143 offset:2560
	ds_read_b32 v219, v143 offset:1600
	ds_read_b32 v235, v143 offset:2624
	ds_read_b32 v220, v143 offset:1664
	ds_read_b32 v236, v143 offset:2688
	ds_read_b32 v221, v143 offset:1728
	ds_read_b32 v237, v143 offset:2752
	s_waitcnt lgkmcnt(0)
	v_mul_f32_e32 v120, v120, v124
	v_mul_f32_e32 v121, v121, v125
	v_mul_f32_e32 v122, v122, v126
	v_mul_f32_e32 v123, v123, v127
	v_mul_f32_e32 v112, v112, v116
	v_mul_f32_e32 v113, v113, v117
	v_mul_f32_e32 v114, v114, v118
	v_mul_f32_e32 v115, v115, v119
	v_mul_f32_e32 v124, v140, v124
	v_mul_f32_e32 v125, v140, v125
	v_mul_f32_e32 v126, v140, v126
	v_mul_f32_e32 v127, v140, v127
	v_mul_f32_e32 v116, v140, v116
	v_mul_f32_e32 v117, v140, v117
	v_mul_f32_e32 v118, v140, v118
	v_mul_f32_e32 v119, v140, v119
	v_exp_f32_e32 v124, v124
	v_exp_f32_e32 v125, v125
	v_exp_f32_e32 v126, v126
	v_exp_f32_e32 v127, v127
	v_exp_f32_e32 v116, v116
	v_exp_f32_e32 v117, v117
	v_exp_f32_e32 v118, v118
	v_exp_f32_e32 v119, v119
	v_fma_f32 v124, v124, v230, v230
	v_fma_f32 v125, v125, v230, v230
	v_fma_f32 v126, v126, v230, v230
	v_fma_f32 v127, v127, v230, v230
	v_fma_f32 v116, v116, v230, v230
	v_fma_f32 v117, v117, v230, v230
	v_fma_f32 v118, v118, v230, v230
	v_fma_f32 v119, v119, v230, v230
	v_rcp_f32_e32 v124, v124
	v_rcp_f32_e32 v125, v125
	v_rcp_f32_e32 v126, v126
	v_rcp_f32_e32 v127, v127
	v_rcp_f32_e32 v116, v116
	v_rcp_f32_e32 v117, v117
	v_rcp_f32_e32 v118, v118
	v_rcp_f32_e32 v119, v119
	v_mul_f32_e32 v120, v120, v124
	v_mul_f32_e32 v121, v121, v125
	v_mul_f32_e32 v122, v122, v126
	v_mul_f32_e32 v123, v123, v127
	v_mul_f32_e32 v112, v112, v116
	v_mul_f32_e32 v113, v113, v117
	v_mul_f32_e32 v114, v114, v118
	v_mul_f32_e32 v115, v115, v119
	v_cvt_pk_bf16_f32 v124, v120, v121
	v_cvt_pk_bf16_f32 v125, v122, v123
	v_cvt_pk_bf16_f32 v126, v112, v113
	v_cvt_pk_bf16_f32 v127, v114, v115
	s_movk_i32 s1, 0xb00
	v_lshl_or_b32 v139, s8, 7, v144
	v_mul_lo_u32 v113, v138, s1
	v_add_lshl_u32 v222, v113, v139, 1
	buffer_store_dwordx4 v[124:127], v222, s[36:39], 0 offen sc1
	v_mul_f32_e32 v104, v104, v108
	v_mul_f32_e32 v105, v105, v109
	v_mul_f32_e32 v106, v106, v110
	v_mul_f32_e32 v107, v107, v111
	v_mul_f32_e32 v96, v96, v100
	v_mul_f32_e32 v97, v97, v101
	v_mul_f32_e32 v98, v98, v102
	v_mul_f32_e32 v99, v99, v103
	v_mul_f32_e32 v108, v215, v108
	v_mul_f32_e32 v109, v215, v109
	v_mul_f32_e32 v110, v215, v110
	v_mul_f32_e32 v111, v215, v111
	v_mul_f32_e32 v100, v215, v100
	v_mul_f32_e32 v101, v215, v101
	v_mul_f32_e32 v102, v215, v102
	v_mul_f32_e32 v103, v215, v103
	v_exp_f32_e32 v108, v108
	v_exp_f32_e32 v109, v109
	v_exp_f32_e32 v110, v110
	v_exp_f32_e32 v111, v111
	v_exp_f32_e32 v100, v100
	v_exp_f32_e32 v101, v101
	v_exp_f32_e32 v102, v102
	v_exp_f32_e32 v103, v103
	v_fma_f32 v108, v108, v231, v231
	v_fma_f32 v109, v109, v231, v231
	v_fma_f32 v110, v110, v231, v231
	v_fma_f32 v111, v111, v231, v231
	v_fma_f32 v100, v100, v231, v231
	v_fma_f32 v101, v101, v231, v231
	v_fma_f32 v102, v102, v231, v231
	v_fma_f32 v103, v103, v231, v231
	v_rcp_f32_e32 v108, v108
	v_rcp_f32_e32 v109, v109
	v_rcp_f32_e32 v110, v110
	v_rcp_f32_e32 v111, v111
	v_rcp_f32_e32 v100, v100
	v_rcp_f32_e32 v101, v101
	v_rcp_f32_e32 v102, v102
	v_rcp_f32_e32 v103, v103
	v_mul_f32_e32 v104, v104, v108
	v_mul_f32_e32 v105, v105, v109
	v_mul_f32_e32 v106, v106, v110
	v_mul_f32_e32 v107, v107, v111
	v_mul_f32_e32 v96, v96, v100
	v_mul_f32_e32 v97, v97, v101
	v_mul_f32_e32 v98, v98, v102
	v_mul_f32_e32 v99, v99, v103
	v_cvt_pk_bf16_f32 v108, v104, v105
	v_cvt_pk_bf16_f32 v109, v106, v107
	v_cvt_pk_bf16_f32 v110, v96, v97
	v_cvt_pk_bf16_f32 v111, v98, v99
	s_mov_b32 s1, 0x16000
	buffer_store_dwordx4 v[108:111], v222, s[36:39], s1 offen sc1
	s_nop 1
	v_mul_f32_e32 v88, v88, v92
	v_mul_f32_e32 v89, v89, v93
	v_mul_f32_e32 v90, v90, v94
	v_mul_f32_e32 v91, v91, v95
	v_mul_f32_e32 v80, v80, v84
	v_mul_f32_e32 v81, v81, v85
	v_mul_f32_e32 v82, v82, v86
	v_mul_f32_e32 v83, v83, v87
	v_mul_f32_e32 v92, v216, v92
	v_mul_f32_e32 v93, v216, v93
	v_mul_f32_e32 v94, v216, v94
	v_mul_f32_e32 v95, v216, v95
	v_mul_f32_e32 v84, v216, v84
	v_mul_f32_e32 v85, v216, v85
	v_mul_f32_e32 v86, v216, v86
	v_mul_f32_e32 v87, v216, v87
	v_exp_f32_e32 v92, v92
	v_exp_f32_e32 v93, v93
	v_exp_f32_e32 v94, v94
	v_exp_f32_e32 v95, v95
	v_exp_f32_e32 v84, v84
	v_exp_f32_e32 v85, v85
	v_exp_f32_e32 v86, v86
	v_exp_f32_e32 v87, v87
	v_fma_f32 v92, v92, v232, v232
	v_fma_f32 v93, v93, v232, v232
	v_fma_f32 v94, v94, v232, v232
	v_fma_f32 v95, v95, v232, v232
	v_fma_f32 v84, v84, v232, v232
	v_fma_f32 v85, v85, v232, v232
	v_fma_f32 v86, v86, v232, v232
	v_fma_f32 v87, v87, v232, v232
	v_rcp_f32_e32 v92, v92
	v_rcp_f32_e32 v93, v93
	v_rcp_f32_e32 v94, v94
	v_rcp_f32_e32 v95, v95
	v_rcp_f32_e32 v84, v84
	v_rcp_f32_e32 v85, v85
	v_rcp_f32_e32 v86, v86
	v_rcp_f32_e32 v87, v87
	v_mul_f32_e32 v88, v88, v92
	v_mul_f32_e32 v89, v89, v93
	v_mul_f32_e32 v90, v90, v94
	v_mul_f32_e32 v91, v91, v95
	v_mul_f32_e32 v80, v80, v84
	v_mul_f32_e32 v81, v81, v85
	v_mul_f32_e32 v82, v82, v86
	v_mul_f32_e32 v83, v83, v87
	v_cvt_pk_bf16_f32 v92, v88, v89
	v_cvt_pk_bf16_f32 v93, v90, v91
	v_cvt_pk_bf16_f32 v94, v80, v81
	v_cvt_pk_bf16_f32 v95, v82, v83
	s_mov_b32 s1, 0x2c000
	buffer_store_dwordx4 v[92:95], v222, s[36:39], s1 offen sc1
	s_nop 1
	v_mul_f32_e32 v72, v72, v76
	v_mul_f32_e32 v73, v73, v77
	v_mul_f32_e32 v74, v74, v78
	v_mul_f32_e32 v75, v75, v79
	v_mul_f32_e32 v64, v64, v68
	v_mul_f32_e32 v65, v65, v69
	v_mul_f32_e32 v66, v66, v70
	v_mul_f32_e32 v67, v67, v71
	v_mul_f32_e32 v76, v217, v76
	v_mul_f32_e32 v77, v217, v77
	v_mul_f32_e32 v78, v217, v78
	v_mul_f32_e32 v79, v217, v79
	v_mul_f32_e32 v68, v217, v68
	v_mul_f32_e32 v69, v217, v69
	v_mul_f32_e32 v70, v217, v70
	v_mul_f32_e32 v71, v217, v71
	v_exp_f32_e32 v76, v76
	v_exp_f32_e32 v77, v77
	v_exp_f32_e32 v78, v78
	v_exp_f32_e32 v79, v79
	v_exp_f32_e32 v68, v68
	v_exp_f32_e32 v69, v69
	v_exp_f32_e32 v70, v70
	v_exp_f32_e32 v71, v71
	v_fma_f32 v76, v76, v233, v233
	v_fma_f32 v77, v77, v233, v233
	v_fma_f32 v78, v78, v233, v233
	v_fma_f32 v79, v79, v233, v233
	v_fma_f32 v68, v68, v233, v233
	v_fma_f32 v69, v69, v233, v233
	v_fma_f32 v70, v70, v233, v233
	v_fma_f32 v71, v71, v233, v233
	v_rcp_f32_e32 v76, v76
	v_rcp_f32_e32 v77, v77
	v_rcp_f32_e32 v78, v78
	v_rcp_f32_e32 v79, v79
	v_rcp_f32_e32 v68, v68
	v_rcp_f32_e32 v69, v69
	v_rcp_f32_e32 v70, v70
	v_rcp_f32_e32 v71, v71
	v_mul_f32_e32 v72, v72, v76
	v_mul_f32_e32 v73, v73, v77
	v_mul_f32_e32 v74, v74, v78
	v_mul_f32_e32 v75, v75, v79
	v_mul_f32_e32 v64, v64, v68
	v_mul_f32_e32 v65, v65, v69
	v_mul_f32_e32 v66, v66, v70
	v_mul_f32_e32 v67, v67, v71
	v_cvt_pk_bf16_f32 v76, v72, v73
	v_cvt_pk_bf16_f32 v77, v74, v75
	v_cvt_pk_bf16_f32 v78, v64, v65
	v_cvt_pk_bf16_f32 v79, v66, v67
	s_mov_b32 s1, 0x42000
	buffer_store_dwordx4 v[76:79], v222, s[36:39], s1 offen sc1
	s_nop 1
	v_mul_f32_e32 v56, v56, v60
	v_mul_f32_e32 v57, v57, v61
	v_mul_f32_e32 v58, v58, v62
	v_mul_f32_e32 v59, v59, v63
	v_mul_f32_e32 v48, v48, v52
	v_mul_f32_e32 v49, v49, v53
	v_mul_f32_e32 v50, v50, v54
	v_mul_f32_e32 v51, v51, v55
	v_mul_f32_e32 v60, v218, v60
	v_mul_f32_e32 v61, v218, v61
	v_mul_f32_e32 v62, v218, v62
	v_mul_f32_e32 v63, v218, v63
	v_mul_f32_e32 v52, v218, v52
	v_mul_f32_e32 v53, v218, v53
	v_mul_f32_e32 v54, v218, v54
	v_mul_f32_e32 v55, v218, v55
	v_exp_f32_e32 v60, v60
	v_exp_f32_e32 v61, v61
	v_exp_f32_e32 v62, v62
	v_exp_f32_e32 v63, v63
	v_exp_f32_e32 v52, v52
	v_exp_f32_e32 v53, v53
	v_exp_f32_e32 v54, v54
	v_exp_f32_e32 v55, v55
	v_fma_f32 v60, v60, v234, v234
	v_fma_f32 v61, v61, v234, v234
	v_fma_f32 v62, v62, v234, v234
	v_fma_f32 v63, v63, v234, v234
	v_fma_f32 v52, v52, v234, v234
	v_fma_f32 v53, v53, v234, v234
	v_fma_f32 v54, v54, v234, v234
	v_fma_f32 v55, v55, v234, v234
	v_rcp_f32_e32 v60, v60
	v_rcp_f32_e32 v61, v61
	v_rcp_f32_e32 v62, v62
	v_rcp_f32_e32 v63, v63
	v_rcp_f32_e32 v52, v52
	v_rcp_f32_e32 v53, v53
	v_rcp_f32_e32 v54, v54
	v_rcp_f32_e32 v55, v55
	v_mul_f32_e32 v56, v56, v60
	v_mul_f32_e32 v57, v57, v61
	v_mul_f32_e32 v58, v58, v62
	v_mul_f32_e32 v59, v59, v63
	v_mul_f32_e32 v48, v48, v52
	v_mul_f32_e32 v49, v49, v53
	v_mul_f32_e32 v50, v50, v54
	v_mul_f32_e32 v51, v51, v55
	v_cvt_pk_bf16_f32 v60, v56, v57
	v_cvt_pk_bf16_f32 v61, v58, v59
	v_cvt_pk_bf16_f32 v62, v48, v49
	v_cvt_pk_bf16_f32 v63, v50, v51
	s_mov_b32 s1, 0xb0000
	buffer_store_dwordx4 v[60:63], v222, s[36:39], s1 offen sc1
	s_nop 1
	v_mul_f32_e32 v40, v40, v44
	v_mul_f32_e32 v41, v41, v45
	v_mul_f32_e32 v42, v42, v46
	v_mul_f32_e32 v43, v43, v47
	v_mul_f32_e32 v32, v32, v36
	v_mul_f32_e32 v33, v33, v37
	v_mul_f32_e32 v34, v34, v38
	v_mul_f32_e32 v35, v35, v39
	v_mul_f32_e32 v44, v219, v44
	v_mul_f32_e32 v45, v219, v45
	v_mul_f32_e32 v46, v219, v46
	v_mul_f32_e32 v47, v219, v47
	v_mul_f32_e32 v36, v219, v36
	v_mul_f32_e32 v37, v219, v37
	v_mul_f32_e32 v38, v219, v38
	v_mul_f32_e32 v39, v219, v39
	v_exp_f32_e32 v44, v44
	v_exp_f32_e32 v45, v45
	v_exp_f32_e32 v46, v46
	v_exp_f32_e32 v47, v47
	v_exp_f32_e32 v36, v36
	v_exp_f32_e32 v37, v37
	v_exp_f32_e32 v38, v38
	v_exp_f32_e32 v39, v39
	v_fma_f32 v44, v44, v235, v235
	v_fma_f32 v45, v45, v235, v235
	v_fma_f32 v46, v46, v235, v235
	v_fma_f32 v47, v47, v235, v235
	v_fma_f32 v36, v36, v235, v235
	v_fma_f32 v37, v37, v235, v235
	v_fma_f32 v38, v38, v235, v235
	v_fma_f32 v39, v39, v235, v235
	v_rcp_f32_e32 v44, v44
	v_rcp_f32_e32 v45, v45
	v_rcp_f32_e32 v46, v46
	v_rcp_f32_e32 v47, v47
	v_rcp_f32_e32 v36, v36
	v_rcp_f32_e32 v37, v37
	v_rcp_f32_e32 v38, v38
	v_rcp_f32_e32 v39, v39
	v_mul_f32_e32 v40, v40, v44
	v_mul_f32_e32 v41, v41, v45
	v_mul_f32_e32 v42, v42, v46
	v_mul_f32_e32 v43, v43, v47
	v_mul_f32_e32 v32, v32, v36
	v_mul_f32_e32 v33, v33, v37
	v_mul_f32_e32 v34, v34, v38
	v_mul_f32_e32 v35, v35, v39
	v_cvt_pk_bf16_f32 v44, v40, v41
	v_cvt_pk_bf16_f32 v45, v42, v43
	v_cvt_pk_bf16_f32 v46, v32, v33
	v_cvt_pk_bf16_f32 v47, v34, v35
	s_mov_b32 s1, 0xc6000
	buffer_store_dwordx4 v[44:47], v222, s[36:39], s1 offen sc1
	v_mul_f32_e32 v24, v24, v28
	v_mul_f32_e32 v25, v25, v29
	v_mul_f32_e32 v26, v26, v30
	v_mul_f32_e32 v27, v27, v31
	v_mul_f32_e32 v16, v16, v20
	v_mul_f32_e32 v17, v17, v21
	v_mul_f32_e32 v18, v18, v22
	v_mul_f32_e32 v19, v19, v23
	v_mul_f32_e32 v28, v220, v28
	v_mul_f32_e32 v29, v220, v29
	v_mul_f32_e32 v30, v220, v30
	v_mul_f32_e32 v31, v220, v31
	v_mul_f32_e32 v20, v220, v20
	v_mul_f32_e32 v21, v220, v21
	v_mul_f32_e32 v22, v220, v22
	v_mul_f32_e32 v23, v220, v23
	v_exp_f32_e32 v28, v28
	v_exp_f32_e32 v29, v29
	v_exp_f32_e32 v30, v30
	v_exp_f32_e32 v31, v31
	v_exp_f32_e32 v20, v20
	v_exp_f32_e32 v21, v21
	v_exp_f32_e32 v22, v22
	v_exp_f32_e32 v23, v23
	v_fma_f32 v28, v28, v236, v236
	v_fma_f32 v29, v29, v236, v236
	v_fma_f32 v30, v30, v236, v236
	v_fma_f32 v31, v31, v236, v236
	v_fma_f32 v20, v20, v236, v236
	v_fma_f32 v21, v21, v236, v236
	v_fma_f32 v22, v22, v236, v236
	v_fma_f32 v23, v23, v236, v236
	v_rcp_f32_e32 v28, v28
	v_rcp_f32_e32 v29, v29
	v_rcp_f32_e32 v30, v30
	v_rcp_f32_e32 v31, v31
	v_rcp_f32_e32 v20, v20
	v_rcp_f32_e32 v21, v21
	v_rcp_f32_e32 v22, v22
	v_rcp_f32_e32 v23, v23
	v_mul_f32_e32 v24, v24, v28
	v_mul_f32_e32 v25, v25, v29
	v_mul_f32_e32 v26, v26, v30
	v_mul_f32_e32 v27, v27, v31
	v_mul_f32_e32 v16, v16, v20
	v_mul_f32_e32 v17, v17, v21
	v_mul_f32_e32 v18, v18, v22
	v_mul_f32_e32 v19, v19, v23
	v_cvt_pk_bf16_f32 v28, v24, v25
	v_cvt_pk_bf16_f32 v29, v26, v27
	v_cvt_pk_bf16_f32 v30, v16, v17
	v_cvt_pk_bf16_f32 v31, v18, v19
	s_mov_b32 s1, 0xdc000
	buffer_store_dwordx4 v[28:31], v222, s[36:39], s1 offen sc1
	s_nop 1
	s_branch .LBB0_788
